# GEMM phase prologue: the second K-tile's stage loads issued behind the first K-tile's, first wait vmcnt(8)
# baseline (speedup 1.0000x reference)
.LBB0_118:
	s_andn2_b64 vcc, exec, s[28:29]
	s_cbranch_vccnz .LBB0_225
	v_bfe_i32 v3, v15, 27, 1
	v_lshlrev_b32_e32 v1, 4, v15
	v_lshrrev_b32_e32 v3, 22, v3
	v_add_u32_e32 v3, v1, v3
	v_and_b32_e32 v3, 0xfffffc00, v3
	v_sub_u32_e32 v3, v1, v3
	v_lshrrev_b32_e32 v4, 4, v3
	v_ashrrev_i32_e32 v2, 31, v15
	v_bitop3_b32 v3, v4, v3, 32 bitop3:0x6c
	v_lshrrev_b32_e32 v2, 26, v2
	v_ashrrev_i32_e32 v5, 31, v3
	v_add_u32_e32 v2, v15, v2
	v_lshrrev_b32_e32 v5, 26, v5
	v_ashrrev_i32_e32 v2, 6, v2
	v_add_u32_e32 v5, v3, v5
	v_lshlrev_b32_e32 v4, 3, v2
	v_ashrrev_i32_e32 v6, 6, v5
	v_and_b32_e32 v5, 0xc0, v5
	v_and_b32_e32 v4, -16, v4
	v_lshlrev_b32_e32 v2, 5, v2
	v_sub_u32_e32 v3, v3, v5
	v_mov_b32_e32 v8, 1
	v_add_u32_e32 v4, v6, v4
	v_and_b32_e32 v2, 32, v2
	v_ashrrev_i16_sdwa v3, v8, sext(v3) dst_sel:DWORD dst_unused:UNUSED_PAD src0_sel:DWORD src1_sel:BYTE_0
	v_add_u32_sdwa v2, v2, sext(v3) dst_sel:DWORD dst_unused:UNUSED_PAD src0_sel:DWORD src1_sel:WORD_0
	v_lshlrev_b32_e32 v3, 1, v4
	v_lshrrev_b32_e32 v5, 2, v4
	v_and_b32_e32 v6, 3, v6
	s_mov_b32 s3, 0x7fffffe0
	v_and_b32_e32 v3, 24, v3
	v_and_b32_e32 v5, 4, v5
	v_and_or_b32 v6, v4, s3, v6
	v_or3_b32 v3, v6, v5, v3
	v_lshlrev_b32_e32 v6, 2, v4
	v_and_b32_e32 v5, 0xffffffc0, v4
	v_and_b32_e32 v6, 60, v6
	v_bfe_u32 v7, v4, 4, 2
	v_or3_b32 v5, v6, v5, v7
	v_cndmask_b32_e64 v4, v5, v4, s[40:41]
	v_mul_lo_u32 v4, v4, s10
	v_mul_lo_u32 v3, v3, s10
	v_add_u32_e32 v1, 0x2000, v1
	v_add_lshl_u32 v164, v4, v2, 1
	v_add_lshl_u32 v166, v3, v2, 1
	v_ashrrev_i32_e32 v2, 31, v1
	v_lshrrev_b32_e32 v2, 22, v2
	v_add_u32_e32 v2, v1, v2
	v_ashrrev_i32_e32 v2, 10, v2
	v_mul_i32_i24_e32 v3, 0x400, v2
	v_sub_u32_e32 v1, v1, v3
	v_lshrrev_b32_e32 v3, 4, v1
	v_bitop3_b32 v1, v3, v1, 32 bitop3:0x6c
	v_ashrrev_i32_e32 v4, 31, v1
	v_lshrrev_b32_e32 v4, 26, v4
	v_lshlrev_b32_e32 v3, 3, v2
	v_add_u32_e32 v4, v1, v4
	v_and_b32_e32 v3, -16, v3
	v_ashrrev_i32_e32 v5, 6, v4
	v_add_u32_e32 v3, v5, v3
	v_and_b32_e32 v5, 3, v5
	s_lshl_b32 s96, s10, 8
	v_and_or_b32 v5, v3, s3, v5
	s_lshl_b64 s[70:71], s[96:97], 1
	s_ashr_i32 s3, s69, 31
	s_mul_i32 s3, s70, s3
	s_mul_hi_u32 s9, s70, s69
	s_add_i32 s3, s9, s3
	s_bfe_u32 s9, s10, 0x10017
	s_mul_i32 s28, s9, s69
	s_add_i32 s30, s3, s28
	s_ashr_i32 s3, s54, 31
	v_and_b32_e32 v4, 0xc0, v4
	s_mul_i32 s3, s70, s3
	s_mul_hi_u32 s28, s70, s54
	s_ashr_i32 s11, s25, 6
	v_lshlrev_b32_e32 v2, 5, v2
	v_sub_u32_e32 v1, v1, v4
	s_add_i32 s3, s28, s3
	s_mul_i32 s9, s9, s54
	v_and_b32_e32 v2, 32, v2
	v_ashrrev_i16_sdwa v1, v8, sext(v1) dst_sel:DWORD dst_unused:UNUSED_PAD src0_sel:DWORD src1_sel:BYTE_0
	s_ashr_i32 s76, s25, 8
	s_lshl_b32 s77, s11, 10
	s_add_i32 s3, s3, s9
	s_mul_i32 s9, s70, s54
	v_add_u32_sdwa v1, v2, sext(v1) dst_sel:DWORD dst_unused:UNUSED_PAD src0_sel:DWORD src1_sel:WORD_0
	v_lshlrev_b32_e32 v2, 1, v3
	v_lshrrev_b32_e32 v4, 2, v3
	s_add_u32 s88, s14, s9
	v_and_b32_e32 v2, 24, v2
	v_and_b32_e32 v4, 4, v4
	s_addc_u32 s89, s15, s3
	s_add_i32 s3, s77, 0
	v_or3_b32 v2, v5, v4, v2
	s_add_i32 m0, s3, 0x10000
	v_mul_lo_u32 v2, v2, s10
	global_load_lds_dwordx4 v166, s[88:89]
	s_add_i32 m0, s3, 0x12000
	v_add_lshl_u32 v170, v2, v1, 1
	s_add_u32 s28, s88, s96
	v_lshlrev_b32_e32 v5, 2, v3
	global_load_lds_dwordx4 v170, s[88:89]
	s_addc_u32 s29, s89, 0
	s_add_i32 m0, s3, 0x14000
	v_and_b32_e32 v4, 0xffffffc0, v3
	v_and_b32_e32 v5, 60, v5
	v_bfe_u32 v6, v3, 4, 2
	s_mul_i32 s31, s70, s69
	global_load_lds_dwordx4 v166, s[28:29]
	s_add_i32 m0, s3, 0x16000
	v_or3_b32 v4, v5, v4, v6
	s_add_u32 s38, s12, s31
	v_cndmask_b32_e64 v3, v4, v3, s[40:41]
	s_addc_u32 s39, s13, s30
	s_add_i32 s78, s3, 0x2000
	v_mul_lo_u32 v3, v3, s10
	global_load_lds_dwordx4 v170, s[28:29]
	s_mov_b32 m0, s3
	s_add_u32 s30, s38, s96
	v_add_lshl_u32 v168, v3, v1, 1
	global_load_lds_dwordx4 v164, s[38:39]
	s_mov_b32 m0, s78
	s_addc_u32 s31, s39, 0
	s_add_i32 s9, s3, 0x4000
	global_load_lds_dwordx4 v168, s[38:39]
	s_mov_b32 m0, s9
	s_add_i32 s86, s3, 0x6000
	global_load_lds_dwordx4 v164, s[30:31]
	s_mov_b32 m0, s86
	v_writelane_b32 v255, s46, 5
	global_load_lds_dwordx4 v168, s[30:31]
	s_nop 0
	v_writelane_b32 v255, s47, 6
	v_writelane_b32 v255, s44, 7
	v_mov_b32_e32 v167, v0
	v_mov_b32_e32 v171, v0
	v_writelane_b32 v255, s45, 8
	v_writelane_b32 v255, s42, 9
	v_mov_b32_e32 v165, v0
	v_mov_b32_e32 v169, v0
	v_writelane_b32 v255, s43, 10
	v_lshl_add_u64 v[10:11], s[88:89], 0, v[166:167]
	v_lshl_add_u64 v[6:7], s[88:89], 0, v[170:171]
	v_lshl_add_u64 v[4:5], s[28:29], 0, v[166:167]
	v_lshl_add_u64 v[2:3], s[28:29], 0, v[170:171]
	v_lshl_add_u64 v[8:9], s[38:39], 0, v[164:165]
	v_lshl_add_u64 v[12:13], s[38:39], 0, v[168:169]
	s_add_i32 m0, s3, 0x18000
	v_lshl_add_u64 v[10:11], v[10:11], 0, s[4:5]
	global_load_lds_dwordx4 v[10:11], off
	v_lshl_add_u64 v[6:7], v[6:7], 0, s[4:5]
	s_add_i32 m0, s3, 0x1a000
	s_add_i32 s80, s3, 0x8000
	global_load_lds_dwordx4 v[6:7], off
	v_lshl_add_u64 v[6:7], v[8:9], 0, s[4:5]
	s_mov_b32 m0, s80
	s_add_i32 s84, s3, 0xa000
	global_load_lds_dwordx4 v[6:7], off
	v_lshl_add_u64 v[6:7], v[12:13], 0, s[4:5]
	s_mov_b32 m0, s84
	v_lshl_add_u64 v[4:5], v[4:5], 0, s[4:5]
	global_load_lds_dwordx4 v[6:7], off
	s_add_i32 m0, s3, 0x1c000
	v_lshl_add_u64 v[2:3], v[2:3], 0, s[4:5]
	global_load_lds_dwordx4 v[4:5], off
	s_add_i32 m0, s3, 0x1e000
	s_nop 0
	global_load_lds_dwordx4 v[2:3], off
	s_cmp_eq_u32 s76, 1
	s_cselect_b64 s[28:29], -1, 0
	s_cmp_lg_u32 s76, 1
	s_cbranch_scc1 .LBB0_121
	s_barrier
.LBB0_121:
	s_waitcnt vmcnt(8)
	s_barrier
	s_lshl_b32 s11, s11, 5
	v_lshrrev_b32_e32 v2, 1, v15
	v_and_b32_e32 v2, 24, v2
	s_and_b32 s34, s11, 0x60
	v_and_b32_e32 v1, 15, v15
	v_lshlrev_b32_e32 v3, 1, v2
	v_or_b32_e32 v172, s34, v2
	v_rcp_iflag_f32_e32 v2, v14
	v_lshlrev_b32_e32 v241, 2, v1
	s_lshr_b32 s83, s10, 6
	v_lshl_or_b32 v3, v1, 6, v3
	v_and_b32_e32 v4, 32, v241
	s_mov_b32 s100, 0x14000
	s_mov_b32 s11, 7
	s_cmp_eq_u32 s81, 0
	s_cbranch_scc1 .Lfl_remap
	s_cmp_eq_u32 s81, 3
	s_cbranch_scc1 .Lfl_remap
	s_branch .Lfl_noremap
